# diff attention LDS-DMA addresses moved to scalar unit (saddr form), on top of NA sentinel-table body
# speedup vs baseline: 1.0077x; 1.0022x over previous
;     ...
;     const bf16_t* kbase = Kg + (size_t)R0 * 512 + hd * 128;
;     const bf16_t* vbase = Vg + (size_t)R0 * 512 + hd * 128;
;     const size_t g0 = dma_goff(wid, lane, 512), g1 = dma_goff(wid + 8, lane, 512);
;     const unsigned d0 = wid * 1024u, d1 = (wid + 8) * 1024u;
;     const unsigned kb0 = kbase_of(lane), kb1 = kb0 ^ 32u, vb0 = vbase_of(lane), vb1 = vb0 ^ 32u;
;     const int nt = S / 64;
;     ...
;     DIFF_DMA2(0, 0);
;     float mrun = 0.f, lrun = 0.f;
;     f32x16 O[4]; bf16x8 P[4];
; #pragma unroll
;     for (int e = 0; e < 4; ++e) { O[e] = (f32x16){}; P[e] = (bf16x8){}; }
;     const int qidx = q0w + r32;
;     const int ibq = 128 + 4 * hi - qidx;
;     const int ns = nt >> 1;
;     __syncthreads();
;     if (wid < 4) __builtin_amdgcn_s_setprio(1);
.LBB0_198:
	v_lshlrev_b32_e32 v10, 6, v171
	v_lshlrev_b32_e32 v9, 8, v171
	v_and_b32_e32 v10, 0x1c0, v10
	s_movk_i32 s9, 0x1800
	v_lshrrev_b32_e32 v11, 3, v3
	v_bfe_u32 v8, v3, 2, 4
	v_and_or_b32 v9, v9, s9, v10
	v_and_b32_e32 v10, 0xc0, v6
	v_and_b32_e32 v11, 2, v11
	v_bfe_u32 v3, v3, 1, 1
	v_lshlrev_b32_e32 v170, 2, v2
	v_lshlrev_b32_e32 v169, 3, v2
	v_bitop3_b32 v8, v8, v2, 3 bitop3:0x6c
	v_lshl_or_b32 v10, v2, 8, v10
	v_bitop3_b32 v3, v11, v2, v3 bitop3:0x36
	v_add_u32_e32 v2, s30, v0
	v_sub_u32_e32 v0, v170, v0
	v_lshl_or_b32 v3, v3, 4, v10
	v_lshlrev_b32_e32 v10, 3, v171
	v_subrev_u32_e32 v0, s29, v0
	v_and_b32_e32 v10, 8, v10
	v_subrev_u32_e32 v177, s5, v0
	v_add_u32_e32 v0, s35, v4
	v_or_b32_e32 v173, v3, v10
	v_bitop3_b32 v174, v3, 32, v10 bitop3:0x36
	v_sub_u32_e32 v176, v170, v2
	v_lshlrev_b64 v[2:3], 10, v[0:1]
	v_add_u32_e32 v0, s34, v6
	v_lshrrev_b32_e32 v0, 3, v0
	v_lshl_add_u64 v[2:3], s[10:11], 0, v[2:3]
	v_lshlrev_b32_e32 v6, 4, v7
	v_and_b32_e32 v7, 0xc0, v0
	v_or3_b32 v2, v7, v6, v2
	v_add_u32_e32 v0, s31, v4
	v_lshl_add_u64 v[164:165], s[22:23], 0, v[2:3]
	v_lshlrev_b64 v[2:3], 10, v[0:1]
	v_lshl_add_u64 v[2:3], s[10:11], 0, v[2:3]
	v_lshlrev_b32_e32 v0, 4, v5
	s_mul_i32 s8, s4, 0x404
	v_lshlrev_b32_e32 v8, 4, v8
	v_or3_b32 v2, v0, v7, v2
	v_mov_b32_e32 v14, v1
	v_mov_b32_e32 v15, v1
	v_or_b32_e32 v172, v8, v9
	s_add_i32 s25, s8, 0
	v_bitop3_b32 v175, v8, 32, v9 bitop3:0x36
	s_mov_b32 s5, s85
	v_lshl_add_u64 v[166:167], s[22:23], 0, v[2:3]
	v_mov_b32_e32 v0, v1
	v_mov_b32_e32 v2, v1
	v_mov_b32_e32 v3, v1
	v_mov_b32_e32 v4, v1
	v_mov_b32_e32 v5, v1
	v_mov_b32_e32 v6, v1
	v_mov_b32_e32 v7, v1
	v_mov_b32_e32 v8, v1
	v_mov_b32_e32 v9, v1
	v_mov_b32_e32 v10, v1
	v_mov_b32_e32 v11, v1
	v_mov_b32_e32 v12, v1
	v_mov_b32_e32 v13, v1
	v_mov_b64_e32 v[30:31], v[14:15]
	v_mov_b64_e32 v[46:47], v[14:15]
	v_mov_b64_e32 v[62:63], v[14:15]
	v_mov_b64_e32 v[78:79], v[14:15]
	s_add_i32 s25, s25, 0x20000
	s_add_i32 s26, s30, 0x7a
	s_lshl_b32 s27, s18, 10
	s_add_i32 s28, s30, 58
	s_mov_b32 s29, 0
	s_sub_i32 s30, 0, s30
	s_lshl_b64 s[8:9], s[4:5], 8
	s_lshl_b32 s31, s17, 7
	v_mov_b32_e32 v178, 0
	s_mov_b32 s34, 0x10000
	s_mov_b32 s35, 1
	v_mov_b64_e32 v[28:29], v[12:13]
	v_mov_b64_e32 v[26:27], v[10:11]
	v_mov_b64_e32 v[24:25], v[8:9]
	v_mov_b64_e32 v[22:23], v[6:7]
	v_mov_b64_e32 v[20:21], v[4:5]
	v_mov_b64_e32 v[18:19], v[2:3]
	v_mov_b64_e32 v[16:17], v[0:1]
	v_mov_b64_e32 v[44:45], v[12:13]
	v_mov_b64_e32 v[42:43], v[10:11]
	v_mov_b64_e32 v[40:41], v[8:9]
	v_mov_b64_e32 v[38:39], v[6:7]
	v_mov_b64_e32 v[36:37], v[4:5]
	v_mov_b64_e32 v[34:35], v[2:3]
	v_mov_b64_e32 v[32:33], v[0:1]
	v_mov_b64_e32 v[60:61], v[12:13]
	v_mov_b64_e32 v[58:59], v[10:11]
	v_mov_b64_e32 v[56:57], v[8:9]
	v_mov_b64_e32 v[54:55], v[6:7]
	v_mov_b64_e32 v[52:53], v[4:5]
	v_mov_b64_e32 v[50:51], v[2:3]
	v_mov_b64_e32 v[48:49], v[0:1]
	v_mov_b64_e32 v[76:77], v[12:13]
	v_mov_b64_e32 v[74:75], v[10:11]
	v_mov_b64_e32 v[72:73], v[8:9]
	v_mov_b64_e32 v[70:71], v[6:7]
	v_mov_b64_e32 v[68:69], v[4:5]
	v_mov_b64_e32 v[66:67], v[2:3]
	v_mov_b64_e32 v[64:65], v[0:1]
	v_mov_b32_e32 v15, 0
	v_readfirstlane_b32 s10, v166
	v_readfirstlane_b32 s11, v167
	s_nop 1
	v_subrev_u32_e32 v250, s10, v166
	v_subrev_u32_e32 v251, s10, v164
	v_add_u32_e32 v250, 0x1000, v250
	v_add_u32_e32 v251, 0x1000, v251
	s_add_u32 s10, s10, s8
	s_addc_u32 s11, s11, s9
	s_sub_u32 s10, s10, 0x21000
	s_subb_u32 s11, s11, 0
	v_writelane_b32 v247, s10, 0
	v_writelane_b32 v247, s11, 1
	s_branch .LBB0_200
; #define LAS __attribute__((address_space(3)))
; template <bool HAS_QK, bool HAS_PV> ...
;     ...
;     if (HAS_PV) {
; #pragma unroll
;         for (int ks = 0; ks < 2; ++ks)
; #pragma unroll
;             for (int c4 = 0; c4 < 4; ++c4) { const bf16x8 vf = vfrag(Vp, vb0, vb1, ks, c4); O[c4] = __builtin_amdgcn_mfma_f32_32x32x16_bf16(vf, P[ks], O[c4], 0, 0, 0); }
;     }
;     float f = 1.f; bool need = false;
;     if (HAS_QK) {
;         if (NEAR) {
; #pragma unroll
;             for (int r = 0; r < 16; ++r) { int i0 = ib0 + (r & 3) + 8 * (r >> 2), i1 = i0 + 32; i0 = min(max(i0, 0), 256); i1 = min(max(i1, 0), 256); s0[r] += tab[i0]; s1[r] += tab[i1]; }
;         }
;         const float rm = rowmax32(s0, s1);
;         need = first || __any(rm > 8.f);
;         if (need) { const float dl = first ? rm : fmaxf(rm, 0.f); mrun += dl; f = first ? 1.f : __builtin_amdgcn_exp2f(-dl);
; #pragma unroll
;             for (int r = 0; r < 16; ++r) { s0[r] -= dl; s1[r] -= dl; } }
;     }
;     if (HAS_PV) {
; #pragma unroll
;         for (int ks = 2; ks < 4; ++ks)
; #pragma unroll
;             for (int c4 = 0; c4 < 4; ++c4) { const bf16x8 vf = vfrag(Vp, vb0, vb1, ks, c4); O[c4] = __builtin_amdgcn_mfma_f32_32x32x16_bf16(vf, P[ks], O[c4], 0, 0, 0); }
;     }
;     ...
;     for (int st = 0; st < ns; ++st) {
;         const unsigned bb = (st & 1) * 65536u;
;         if (st + 1 < ns) DIFF_DMA2(st + 1, ((st + 1) & 1) * 65536u);
;         const LAS unsigned char* KA = lds + bb + cmap * 1024; const LAS unsigned char* VA = lds + bb + 16384;
;         const LAS unsigned char* KB = lds + bb + 32768 + cmap * 1024; const LAS unsigned char* VB = lds + bb + 49152;
;         { const int kq = st * 128;
;           const bool farR = (kq - q0w - 31 >= 91), farL = (kq + 63 - q0w <= -91), nr = !(farR || farL);
;           diff_step<true, false>(KA, VA, tab, qf, O, P, mrun, lrun, nr ? 0.f : (farR ? tab[256] : tab[0]), kq + ibq, kb0, kb1, vb0, vb1, nr, st == 0); }
;         { const int kq = st * 128 + 64;
;           const bool farR = (kq - q0w - 31 >= 91), farL = (kq + 63 - q0w <= -91), nr = !(farR || farL);
;           diff_step<true, true>(KB, VA, tab, qf, O, P, mrun, lrun, nr ? 0.f : (farR ? tab[256] : tab[0]), kq + ibq, kb0, kb1, vb0, vb1, nr); }
;         diff_step<false, true>(KB, VB, tab, qf, O, P, mrun, lrun, 0.f, 0, kb0, kb1, vb0, vb1, false);
;         __syncthreads();
;     }
.LBB0_199:
	ds_read_b64_tr_b16 v[220:221], v237 offset:49152
	ds_read_b64_tr_b16 v[222:223], v236 offset:51200
	ds_read_b64_tr_b16 v[224:225], v237 offset:49664
	ds_read_b64_tr_b16 v[226:227], v236 offset:51712
	ds_read_b64_tr_b16 v[228:229], v237 offset:50176
	ds_read_b64_tr_b16 v[230:231], v236 offset:52224
	ds_read_b64_tr_b16 v[232:233], v237 offset:50688
	ds_read_b64_tr_b16 v[234:235], v236 offset:52736
	s_waitcnt lgkmcnt(6)
	v_mfma_f32_32x32x16_bf16 v[64:79], v[220:223], v[182:185], v[64:79]
	ds_read_b64_tr_b16 v[220:221], v237 offset:53248
	ds_read_b64_tr_b16 v[222:223], v236 offset:55296
	v_cvt_pk_bf16_f32 v186, v120, v121
	v_cvt_pk_bf16_f32 v187, v122, v123
	v_cvt_pk_bf16_f32 v188, v124, v125
	v_cvt_pk_bf16_f32 v189, v126, v127
	v_exp_f32_e32 v96, v96
	v_exp_f32_e32 v97, v97
	s_waitcnt lgkmcnt(6)
	v_mfma_f32_32x32x16_bf16 v[48:63], v[224:227], v[182:185], v[48:63]
	ds_read_b64_tr_b16 v[224:225], v237 offset:53760
	ds_read_b64_tr_b16 v[226:227], v236 offset:55808
	v_exp_f32_e32 v98, v98
	v_exp_f32_e32 v99, v99
	v_exp_f32_e32 v100, v100
	s_waitcnt lgkmcnt(6)
	v_mfma_f32_32x32x16_bf16 v[32:47], v[228:231], v[182:185], v[32:47]
	ds_read_b64_tr_b16 v[228:229], v237 offset:54272
	ds_read_b64_tr_b16 v[230:231], v236 offset:56320
	v_exp_f32_e32 v101, v101
	v_exp_f32_e32 v102, v102
	v_exp_f32_e32 v103, v103
	v_cvt_pk_bf16_f32 v10, v96, v97
	v_cvt_pk_bf16_f32 v11, v98, v99
	s_waitcnt lgkmcnt(6)
	v_mfma_f32_32x32x16_bf16 v[16:31], v[232:235], v[182:185], v[16:31]
	ds_read_b64_tr_b16 v[232:233], v237 offset:54784
	ds_read_b64_tr_b16 v[234:235], v236 offset:56832
	v_cvt_pk_bf16_f32 v12, v100, v101
	v_cvt_pk_bf16_f32 v13, v102, v103
	v_exp_f32_e32 v104, v104
	v_exp_f32_e32 v105, v105
	v_exp_f32_e32 v106, v106
	s_waitcnt lgkmcnt(6)
	v_mfma_f32_32x32x16_bf16 v[64:79], v[220:223], v[186:189], v[64:79]
	ds_read_b64_tr_b16 v[220:221], v237 offset:57344
	ds_read_b64_tr_b16 v[222:223], v236 offset:59392
	v_exp_f32_e32 v107, v107
	v_exp_f32_e32 v108, v108
	v_exp_f32_e32 v109, v109
	s_waitcnt lgkmcnt(6)
	v_mfma_f32_32x32x16_bf16 v[48:63], v[224:227], v[186:189], v[48:63]
	ds_read_b64_tr_b16 v[224:225], v237 offset:57856
	ds_read_b64_tr_b16 v[226:227], v236 offset:59904
	v_exp_f32_e32 v110, v110
	v_exp_f32_e32 v111, v111
	v_cvt_pk_bf16_f32 v216, v104, v105
	v_cvt_pk_bf16_f32 v217, v106, v107
	v_cvt_pk_bf16_f32 v218, v108, v109
	v_cvt_pk_bf16_f32 v219, v110, v111
	s_waitcnt lgkmcnt(6)
	v_mfma_f32_32x32x16_bf16 v[32:47], v[228:231], v[186:189], v[32:47]
	ds_read_b64_tr_b16 v[228:229], v237 offset:58368
	ds_read_b64_tr_b16 v[230:231], v236 offset:60416
	v_add_f32_e32 v210, v179, v180
	v_add_f32_e32 v211, v80, v81
	v_add_f32_e32 v212, v112, v113
	v_add_f32_e32 v213, v96, v97
	v_add_f32_e32 v210, v130, v210
	v_add_f32_e32 v211, v82, v211
	v_add_f32_e32 v212, v114, v212
	s_waitcnt lgkmcnt(6)
	v_mfma_f32_32x32x16_bf16 v[16:31], v[232:235], v[186:189], v[16:31]
	ds_read_b64_tr_b16 v[232:233], v237 offset:58880
	ds_read_b64_tr_b16 v[234:235], v236 offset:60928
	v_add_f32_e32 v213, v98, v213
	v_add_f32_e32 v210, v131, v210
	v_add_f32_e32 v211, v83, v211
	v_add_f32_e32 v212, v115, v212
	v_add_f32_e32 v213, v99, v213
	v_add_f32_e32 v210, v132, v210
	v_add_f32_e32 v211, v84, v211
	v_add_f32_e32 v212, v116, v212
	s_waitcnt lgkmcnt(6)
	v_mfma_f32_32x32x16_bf16 v[64:79], v[220:223], v[10:13], v[64:79]
	ds_read_b64_tr_b16 v[220:221], v237 offset:61440
	ds_read_b64_tr_b16 v[222:223], v236 offset:63488
	v_add_f32_e32 v213, v100, v213
	v_add_f32_e32 v210, v133, v210
	v_add_f32_e32 v211, v85, v211
	v_add_f32_e32 v212, v117, v212
	v_add_f32_e32 v213, v101, v213
	v_add_f32_e32 v210, v134, v210
	v_add_f32_e32 v211, v86, v211
	s_waitcnt lgkmcnt(6)
	v_mfma_f32_32x32x16_bf16 v[48:63], v[224:227], v[10:13], v[48:63]
	ds_read_b64_tr_b16 v[224:225], v237 offset:61952
	ds_read_b64_tr_b16 v[226:227], v236 offset:64000
	v_add_f32_e32 v212, v118, v212
	v_add_f32_e32 v213, v102, v213
	v_add_f32_e32 v210, v135, v210
	v_add_f32_e32 v211, v87, v211
	v_add_f32_e32 v212, v119, v212
	v_add_f32_e32 v213, v103, v213
	v_add_f32_e32 v210, v136, v210
	s_waitcnt lgkmcnt(6)
	v_mfma_f32_32x32x16_bf16 v[32:47], v[228:231], v[10:13], v[32:47]
	ds_read_b64_tr_b16 v[228:229], v237 offset:62464
	ds_read_b64_tr_b16 v[230:231], v236 offset:64512
	v_add_f32_e32 v211, v88, v211
	v_add_f32_e32 v212, v120, v212
	v_add_f32_e32 v213, v104, v213
	v_add_f32_e32 v210, v137, v210
	v_add_f32_e32 v211, v89, v211
	v_add_f32_e32 v212, v121, v212
	v_add_f32_e32 v213, v105, v213
	v_add_f32_e32 v210, v138, v210
	s_waitcnt lgkmcnt(6)
	v_mfma_f32_32x32x16_bf16 v[16:31], v[232:235], v[10:13], v[16:31]
	ds_read_b64_tr_b16 v[232:233], v237 offset:62976
	ds_read_b64_tr_b16 v[234:235], v236 offset:65024
	v_add_f32_e32 v211, v90, v211
	v_add_f32_e32 v212, v122, v212
	v_add_f32_e32 v213, v106, v213
	v_add_f32_e32 v210, v139, v210
	v_add_f32_e32 v211, v91, v211
	v_add_f32_e32 v212, v123, v212
	v_add_f32_e32 v213, v107, v213
	s_waitcnt lgkmcnt(6)
	v_mfma_f32_32x32x16_bf16 v[64:79], v[220:223], v[216:219], v[64:79]
	v_add_f32_e32 v210, v140, v210
	v_add_f32_e32 v211, v92, v211
	v_add_f32_e32 v212, v124, v212
	v_add_f32_e32 v213, v108, v213
	v_add_f32_e32 v210, v141, v210
	v_add_f32_e32 v211, v93, v211
	v_add_f32_e32 v212, v125, v212
	s_waitcnt lgkmcnt(4)
	v_mfma_f32_32x32x16_bf16 v[48:63], v[224:227], v[216:219], v[48:63]
	v_add_f32_e32 v213, v109, v213
	v_add_f32_e32 v210, v142, v210
	v_add_f32_e32 v211, v94, v211
	v_add_f32_e32 v212, v126, v212
	v_add_f32_e32 v213, v110, v213
	v_add_f32_e32 v210, v143, v210
	v_add_f32_e32 v211, v95, v211
	v_add_f32_e32 v212, v127, v212
	s_waitcnt lgkmcnt(2)
	v_mfma_f32_32x32x16_bf16 v[32:47], v[228:231], v[216:219], v[32:47]
	v_add_f32_e32 v213, v111, v213
	v_add_f32_e32 v210, v210, v211
	v_add_f32_e32 v212, v212, v213
	v_fmac_f32_e32 v210, v178, v0
	v_fma_f32 v178, v210, v14, v212
	s_addk_i32 s29, 0x80
	s_add_i32 s34, s34, 0x10000
	s_add_i32 s35, s35, 1
	s_cmp_eq_u32 s31, s29
	s_waitcnt vmcnt(0) lgkmcnt(0)
	s_barrier
	v_mfma_f32_32x32x16_bf16 v[16:31], v[232:235], v[216:219], v[16:31]
	s_cbranch_scc1 .LBB0_227

; #define LAS __attribute__((address_space(3)))
;     ...
;     DIFF_DMA2(0, 0);
;     float mrun = 0.f, lrun = 0.f;
;     f32x16 O[4]; bf16x8 P[4];
; #pragma unroll
;     for (int e = 0; e < 4; ++e) { O[e] = (f32x16){}; P[e] = (bf16x8){}; }
;     const int qidx = q0w + r32;
;     const int ibq = 128 + 4 * hi - qidx;
;     const int ns = nt >> 1;
;     __syncthreads();
;     if (wid < 4) __builtin_amdgcn_s_setprio(1);
; #pragma unroll 1
;     for (int st = 0; st < ns; ++st) {
;         const unsigned bb = (st & 1) * 65536u;
;         if (st + 1 < ns) DIFF_DMA2(st + 1, ((st + 1) & 1) * 65536u);
;         const LAS unsigned char* KA = lds + bb + cmap * 1024; const LAS unsigned char* VA = lds + bb + 16384;
;         const LAS unsigned char* KB = lds + bb + 32768 + cmap * 1024; const LAS unsigned char* VB = lds + bb + 49152;
;         { const int kq = st * 128;
;           const bool farR = (kq - q0w - 31 >= 91), farL = (kq + 63 - q0w <= -91), nr = !(farR || farL);
;           diff_step<true, false>(KA, VA, tab, qf, O, P, mrun, lrun, nr ? 0.f : (farR ? tab[256] : tab[0]), kq + ibq, kb0, kb1, vb0, vb1, nr, st == 0); }
.LBB0_207:
	s_waitcnt lgkmcnt(0)
	v_sub_f32_e32 v80, v0, v15
	v_mov_b32_e32 v81, v80
	v_mov_b64_e32 v[82:83], v[80:81]
	v_mov_b64_e32 v[84:85], v[80:81]
	v_mov_b64_e32 v[86:87], v[80:81]
	v_mov_b64_e32 v[88:89], v[80:81]
	v_mov_b64_e32 v[90:91], v[80:81]
	v_mov_b64_e32 v[92:93], v[80:81]
	v_mov_b64_e32 v[94:95], v[80:81]
	s_andn2_b64 vcc, exec, s[4:5]
	s_nop 1
	v_mfma_f32_32x32x16_bf16 v[128:143], v[220:223], v[144:147], v[80:95]
	ds_read_b128 v[220:223], v248 offset:512
	v_mfma_f32_32x32x16_bf16 v[80:95], v[224:227], v[144:147], v[80:95]
	ds_read_b128 v[224:227], v248 offset:8704
	v_mfma_f32_32x32x16_bf16 v[128:143], v[228:231], v[148:151], v[128:143]
	ds_read_b128 v[228:231], v249 offset:512
	v_mfma_f32_32x32x16_bf16 v[80:95], v[232:235], v[148:151], v[80:95]
	ds_read_b128 v[232:235], v249 offset:8704
	s_waitcnt lgkmcnt(3)
	v_mfma_f32_32x32x16_bf16 v[128:143], v[220:223], v[152:155], v[128:143]
	s_waitcnt lgkmcnt(2)
	v_mfma_f32_32x32x16_bf16 v[80:95], v[224:227], v[152:155], v[80:95]
	s_waitcnt lgkmcnt(1)
	v_mfma_f32_32x32x16_bf16 v[128:143], v[228:231], v[156:159], v[128:143]
	s_waitcnt lgkmcnt(0)
	v_mfma_f32_32x32x16_bf16 v[80:95], v[232:235], v[156:159], v[80:95]
	ds_read_b128 v[220:223], v248 offset:32768
	ds_read_b128 v[224:227], v249 offset:32768
	ds_read_b128 v[228:231], v248 offset:33280
	ds_read_b128 v[232:235], v249 offset:33280
	s_cmp_ge_u32 s35, s17
	s_cbranch_scc1 .Ldiff_nodma
	s_and_b32 s4, s34, 0x10000
	s_add_i32 s4, s24, s4
	v_readlane_b32 s10, v247, 0
	v_readlane_b32 s11, v247, 1
	s_add_i32 s56, s29, 0x80
	s_lshl_b32 s56, s56, 10
	s_add_u32 s10, s10, s56
	s_addc_u32 s11, s11, 0
	s_add_u32 s56, s10, s72
	s_addc_u32 s57, s11, s73
	s_mov_b32 m0, s4
	s_nop 0
	global_load_lds_dwordx4 v250, s[56:57]
	s_add_i32 m0, s4, 0x2000
	s_nop 0
	global_load_lds_dwordx4 v251, s[56:57]
	s_add_u32 s56, s10, s74
	s_addc_u32 s57, s11, s75
	s_add_i32 m0, s4, 0x4000
	s_nop 0
	global_load_lds_dwordx4 v250, s[56:57]
	s_add_i32 m0, s4, 0x6000
	s_nop 0
	global_load_lds_dwordx4 v251, s[56:57]
	s_add_u32 s56, s10, s68
	s_addc_u32 s57, s11, s69
	s_add_i32 m0, s4, 0x8000
	s_nop 0
	global_load_lds_dwordx4 v250, s[56:57]
	s_add_i32 m0, s4, 0xa000
	s_nop 0
	global_load_lds_dwordx4 v251, s[56:57]
	s_add_u32 s56, s10, s96
	s_addc_u32 s57, s11, s97
	s_add_i32 m0, s4, 0xc000
	s_nop 0
	global_load_lds_dwordx4 v250, s[56:57]
	s_add_i32 m0, s4, 0xe000
	s_nop 0
	global_load_lds_dwordx4 v251, s[56:57]
	s_branch .Ldiff_dma_done
